# grid barrier release flattened: non-leader workgroups poll the cross-XCC generation word directly instead of the per-XCC one
# baseline (speedup 1.0000x reference)
.LBB0_41:
	s_or_b64 exec, exec, s[8:9]
	v_cvt_f32_u32_e32 v4, v2
	s_waitcnt vmcnt(0)
	v_readfirstlane_b32 s6, v3
	v_sub_u32_e32 v3, 0, v2
	v_rcp_iflag_f32_e32 v4, v4
	v_add_u32_e32 v5, s6, v1
	v_mul_f32_e32 v4, 0x4f7ffffe, v4
	v_cvt_u32_f32_e32 v4, v4
	v_mul_lo_u32 v1, v3, v4
	v_mul_hi_u32 v1, v4, v1
	v_add_u32_e32 v1, v4, v1
	v_mul_hi_u32 v1, v5, v1
	v_mul_lo_u32 v3, v1, v2
	v_sub_u32_e32 v3, v5, v3
	v_add_u32_e32 v4, 1, v1
	v_cmp_ge_u32_e32 vcc, v3, v2
	s_nop 1
	v_cndmask_b32_e32 v1, v1, v4, vcc
	v_sub_u32_e32 v4, v3, v2
	v_cndmask_b32_e32 v3, v3, v4, vcc
	v_add_u32_e32 v4, 1, v1
	v_cmp_ge_u32_e32 vcc, v3, v2
	v_add_u32_e32 v3, 1, v5
	s_nop 0
	v_cndmask_b32_e32 v1, v1, v4, vcc
	v_mul_lo_u32 v4, v2, v1
	v_add_u32_e32 v2, v4, v2
	v_cmp_ne_u32_e32 vcc, v3, v2
	s_and_saveexec_b64 s[6:7], vcc
	s_xor_b64 s[6:7], exec, s[6:7]
	s_cbranch_execz .LBB0_55
	s_waitcnt lgkmcnt(0)
	v_mov_b32_e32 v0, 0
	s_add_u32 s14, s74, 0x1e353500
	s_addc_u32 s15, s75, 0
	global_load_dword v0, v0, s[14:15] sc1
	s_waitcnt vmcnt(0)
	v_cmp_eq_u32_e32 vcc, v0, v1
	s_and_saveexec_b64 s[8:9], vcc
	s_cbranch_execz .LBB0_54
	s_add_u32 s10, s74, 0x1e350200
	s_addc_u32 s11, s75, 0
	s_mov_b32 s13, 1
	s_mov_b64 s[34:35], 0
	v_mov_b32_e32 v0, 0
	s_branch .LBB0_45

.LBB0_164:
	s_or_b64 exec, exec, s[8:9]
	v_cvt_f32_u32_e32 v4, v2
	s_waitcnt vmcnt(0)
	v_readfirstlane_b32 s4, v3
	v_sub_u32_e32 v3, 0, v2
	v_rcp_iflag_f32_e32 v4, v4
	v_add_u32_e32 v5, s4, v1
	v_mul_f32_e32 v4, 0x4f7ffffe, v4
	v_cvt_u32_f32_e32 v4, v4
	v_mul_lo_u32 v1, v3, v4
	v_mul_hi_u32 v1, v4, v1
	v_add_u32_e32 v1, v4, v1
	v_mul_hi_u32 v1, v5, v1
	v_mul_lo_u32 v3, v1, v2
	v_sub_u32_e32 v3, v5, v3
	v_add_u32_e32 v4, 1, v1
	v_cmp_ge_u32_e32 vcc, v3, v2
	s_nop 1
	v_cndmask_b32_e32 v1, v1, v4, vcc
	v_sub_u32_e32 v4, v3, v2
	v_cndmask_b32_e32 v3, v3, v4, vcc
	v_add_u32_e32 v4, 1, v1
	v_cmp_ge_u32_e32 vcc, v3, v2
	v_add_u32_e32 v3, 1, v5
	s_nop 0
	v_cndmask_b32_e32 v1, v1, v4, vcc
	v_mul_lo_u32 v4, v2, v1
	v_add_u32_e32 v2, v4, v2
	v_cmp_ne_u32_e32 vcc, v3, v2
	s_and_saveexec_b64 s[4:5], vcc
	s_xor_b64 s[4:5], exec, s[4:5]
	s_cbranch_execz .LBB0_178
	s_waitcnt lgkmcnt(0)
	v_mov_b32_e32 v0, 0
	s_add_u32 s14, s74, 0x1e353500
	s_addc_u32 s15, s75, 0
	global_load_dword v0, v0, s[14:15] sc1
	s_waitcnt vmcnt(0)
	v_cmp_eq_u32_e32 vcc, v0, v1
	s_and_saveexec_b64 s[8:9], vcc
	s_cbranch_execz .LBB0_177
	s_add_u32 s10, s74, 0x1e350200
	s_addc_u32 s11, s75, 0
	s_mov_b32 s13, 1
	s_mov_b64 s[34:35], 0
	v_mov_b32_e32 v0, 0
	s_branch .LBB0_168

.LBB0_306:
	s_or_b64 exec, exec, s[6:7]
	v_cvt_f32_u32_e32 v4, v2
	s_waitcnt vmcnt(0)
	v_readfirstlane_b32 s4, v3
	v_sub_u32_e32 v3, 0, v2
	v_rcp_iflag_f32_e32 v4, v4
	v_add_u32_e32 v5, s4, v1
	v_mul_f32_e32 v4, 0x4f7ffffe, v4
	v_cvt_u32_f32_e32 v4, v4
	v_mul_lo_u32 v1, v3, v4
	v_mul_hi_u32 v1, v4, v1
	v_add_u32_e32 v1, v4, v1
	v_mul_hi_u32 v1, v5, v1
	v_mul_lo_u32 v3, v1, v2
	v_sub_u32_e32 v3, v5, v3
	v_add_u32_e32 v4, 1, v1
	v_cmp_ge_u32_e32 vcc, v3, v2
	s_nop 1
	v_cndmask_b32_e32 v1, v1, v4, vcc
	v_sub_u32_e32 v4, v3, v2
	v_cndmask_b32_e32 v3, v3, v4, vcc
	v_add_u32_e32 v4, 1, v1
	v_cmp_ge_u32_e32 vcc, v3, v2
	v_add_u32_e32 v3, 1, v5
	s_nop 0
	v_cndmask_b32_e32 v1, v1, v4, vcc
	v_mul_lo_u32 v4, v2, v1
	v_add_u32_e32 v2, v4, v2
	v_cmp_ne_u32_e32 vcc, v3, v2
	s_and_saveexec_b64 s[4:5], vcc
	s_xor_b64 s[4:5], exec, s[4:5]
	s_cbranch_execz .LBB0_320
	s_waitcnt lgkmcnt(0)
	v_mov_b32_e32 v0, 0
	s_add_u32 s14, s74, 0x1e353500
	s_addc_u32 s15, s75, 0
	global_load_dword v0, v0, s[14:15] sc1
	s_waitcnt vmcnt(0)
	v_cmp_eq_u32_e32 vcc, v0, v1
	s_and_saveexec_b64 s[6:7], vcc
	s_cbranch_execz .LBB0_319
	s_add_u32 s8, s74, 0x1e350200
	s_addc_u32 s9, s75, 0
	s_mov_b32 s13, 1
	s_mov_b64 s[34:35], 0
	v_mov_b32_e32 v0, 0
	s_branch .LBB0_310

.LBB0_460:
	s_or_b64 exec, exec, s[6:7]
	v_cvt_f32_u32_e32 v4, v2
	s_waitcnt vmcnt(0)
	v_readfirstlane_b32 s4, v3
	v_sub_u32_e32 v3, 0, v2
	v_rcp_iflag_f32_e32 v4, v4
	v_add_u32_e32 v5, s4, v1
	v_mul_f32_e32 v4, 0x4f7ffffe, v4
	v_cvt_u32_f32_e32 v4, v4
	v_mul_lo_u32 v1, v3, v4
	v_mul_hi_u32 v1, v4, v1
	v_add_u32_e32 v1, v4, v1
	v_mul_hi_u32 v1, v5, v1
	v_mul_lo_u32 v3, v1, v2
	v_sub_u32_e32 v3, v5, v3
	v_add_u32_e32 v4, 1, v1
	v_cmp_ge_u32_e32 vcc, v3, v2
	s_nop 1
	v_cndmask_b32_e32 v1, v1, v4, vcc
	v_sub_u32_e32 v4, v3, v2
	v_cndmask_b32_e32 v3, v3, v4, vcc
	v_add_u32_e32 v4, 1, v1
	v_cmp_ge_u32_e32 vcc, v3, v2
	v_add_u32_e32 v3, 1, v5
	s_nop 0
	v_cndmask_b32_e32 v1, v1, v4, vcc
	v_mul_lo_u32 v4, v2, v1
	v_add_u32_e32 v2, v4, v2
	v_cmp_ne_u32_e32 vcc, v3, v2
	s_and_saveexec_b64 s[4:5], vcc
	s_xor_b64 s[4:5], exec, s[4:5]
	s_cbranch_execz .LBB0_474
	s_waitcnt lgkmcnt(0)
	v_mov_b32_e32 v0, 0
	s_add_u32 s10, s74, 0x1e353500
	s_addc_u32 s11, s75, 0
	global_load_dword v0, v0, s[10:11] sc1
	s_waitcnt vmcnt(0)
	v_cmp_eq_u32_e32 vcc, v0, v1
	s_and_saveexec_b64 s[6:7], vcc
	s_cbranch_execz .LBB0_473
	s_add_u32 s8, s74, 0x1e350200
	s_addc_u32 s9, s75, 0
	s_mov_b32 s13, 1
	s_mov_b64 s[14:15], 0
	v_mov_b32_e32 v0, 0
	s_branch .LBB0_464

.LBB0_855:
	s_or_b64 exec, exec, s[8:9]
	v_cvt_f32_u32_e32 v4, v2
	s_waitcnt vmcnt(0)
	v_readfirstlane_b32 s6, v3
	v_sub_u32_e32 v3, 0, v2
	v_rcp_iflag_f32_e32 v4, v4
	v_add_u32_e32 v5, s6, v1
	v_mul_f32_e32 v4, 0x4f7ffffe, v4
	v_cvt_u32_f32_e32 v4, v4
	v_mul_lo_u32 v1, v3, v4
	v_mul_hi_u32 v1, v4, v1
	v_add_u32_e32 v1, v4, v1
	v_mul_hi_u32 v1, v5, v1
	v_mul_lo_u32 v3, v1, v2
	v_sub_u32_e32 v3, v5, v3
	v_add_u32_e32 v4, 1, v1
	v_cmp_ge_u32_e32 vcc, v3, v2
	s_nop 1
	v_cndmask_b32_e32 v1, v1, v4, vcc
	v_sub_u32_e32 v4, v3, v2
	v_cndmask_b32_e32 v3, v3, v4, vcc
	v_add_u32_e32 v4, 1, v1
	v_cmp_ge_u32_e32 vcc, v3, v2
	v_add_u32_e32 v3, 1, v5
	s_nop 0
	v_cndmask_b32_e32 v1, v1, v4, vcc
	v_mul_lo_u32 v4, v2, v1
	v_add_u32_e32 v2, v4, v2
	v_cmp_ne_u32_e32 vcc, v3, v2
	s_and_saveexec_b64 s[6:7], vcc
	s_xor_b64 s[6:7], exec, s[6:7]
	s_cbranch_execz .LBB0_869
	s_waitcnt lgkmcnt(0)
	v_mov_b32_e32 v0, 0
	s_add_u32 s34, s74, 0x1e353500
	s_addc_u32 s35, s75, 0
	global_load_dword v0, v0, s[34:35] sc1
	s_waitcnt vmcnt(0)
	v_cmp_eq_u32_e32 vcc, v0, v1
	s_and_saveexec_b64 s[8:9], vcc
	s_cbranch_execz .LBB0_868
	s_add_u32 s14, s74, 0x1e350200
	s_addc_u32 s15, s75, 0
	s_mov_b32 s13, 1
	s_mov_b64 s[36:37], 0
	v_mov_b32_e32 v0, 0
	s_branch .LBB0_859

.LBB0_1353:
	s_or_b64 exec, exec, s[8:9]
	v_cvt_f32_u32_e32 v4, v2
	s_waitcnt vmcnt(0)
	v_readfirstlane_b32 s4, v3
	v_sub_u32_e32 v3, 0, v2
	v_rcp_iflag_f32_e32 v4, v4
	v_add_u32_e32 v5, s4, v1
	v_mul_f32_e32 v4, 0x4f7ffffe, v4
	v_cvt_u32_f32_e32 v4, v4
	v_mul_lo_u32 v1, v3, v4
	v_mul_hi_u32 v1, v4, v1
	v_add_u32_e32 v1, v4, v1
	v_mul_hi_u32 v1, v5, v1
	v_mul_lo_u32 v3, v1, v2
	v_sub_u32_e32 v3, v5, v3
	v_add_u32_e32 v4, 1, v1
	v_cmp_ge_u32_e32 vcc, v3, v2
	s_nop 1
	v_cndmask_b32_e32 v1, v1, v4, vcc
	v_sub_u32_e32 v4, v3, v2
	v_cndmask_b32_e32 v3, v3, v4, vcc
	v_add_u32_e32 v4, 1, v1
	v_cmp_ge_u32_e32 vcc, v3, v2
	v_add_u32_e32 v3, 1, v5
	s_nop 0
	v_cndmask_b32_e32 v1, v1, v4, vcc
	v_mul_lo_u32 v4, v2, v1
	v_add_u32_e32 v2, v4, v2
	v_cmp_ne_u32_e32 vcc, v3, v2
	s_and_saveexec_b64 s[4:5], vcc
	s_xor_b64 s[4:5], exec, s[4:5]
	s_cbranch_execz .LBB0_1367
	s_waitcnt lgkmcnt(0)
	v_mov_b32_e32 v0, 0
	s_add_u32 s34, s74, 0x1e353500
	s_addc_u32 s35, s75, 0
	global_load_dword v0, v0, s[34:35] sc1
	s_waitcnt vmcnt(0)
	v_cmp_eq_u32_e32 vcc, v0, v1
	s_and_saveexec_b64 s[8:9], vcc
	s_cbranch_execz .LBB0_1366
	s_add_u32 s14, s74, 0x1e350200
	s_addc_u32 s15, s75, 0
	s_mov_b32 s13, 1
	s_mov_b64 s[36:37], 0
	v_mov_b32_e32 v0, 0
	s_branch .LBB0_1357

.LBB0_1482:
	s_or_b64 exec, exec, s[8:9]
	v_cvt_f32_u32_e32 v4, v2
	s_waitcnt vmcnt(0)
	v_readfirstlane_b32 s6, v3
	v_sub_u32_e32 v3, 0, v2
	v_rcp_iflag_f32_e32 v4, v4
	v_add_u32_e32 v5, s6, v1
	v_mul_f32_e32 v4, 0x4f7ffffe, v4
	v_cvt_u32_f32_e32 v4, v4
	v_mul_lo_u32 v1, v3, v4
	v_mul_hi_u32 v1, v4, v1
	v_add_u32_e32 v1, v4, v1
	v_mul_hi_u32 v1, v5, v1
	v_mul_lo_u32 v3, v1, v2
	v_sub_u32_e32 v3, v5, v3
	v_add_u32_e32 v4, 1, v1
	v_cmp_ge_u32_e32 vcc, v3, v2
	s_nop 1
	v_cndmask_b32_e32 v1, v1, v4, vcc
	v_sub_u32_e32 v4, v3, v2
	v_cndmask_b32_e32 v3, v3, v4, vcc
	v_add_u32_e32 v4, 1, v1
	v_cmp_ge_u32_e32 vcc, v3, v2
	v_add_u32_e32 v3, 1, v5
	s_nop 0
	v_cndmask_b32_e32 v1, v1, v4, vcc
	v_mul_lo_u32 v4, v2, v1
	v_add_u32_e32 v2, v4, v2
	v_cmp_ne_u32_e32 vcc, v3, v2
	s_and_saveexec_b64 s[6:7], vcc
	s_xor_b64 s[6:7], exec, s[6:7]
	s_cbranch_execz .LBB0_1496
	s_waitcnt lgkmcnt(0)
	v_mov_b32_e32 v0, 0
	s_add_u32 s16, s74, 0x1e353500
	s_addc_u32 s17, s75, 0
	global_load_dword v0, v0, s[16:17] sc1
	s_waitcnt vmcnt(0)
	v_cmp_eq_u32_e32 vcc, v0, v1
	s_and_saveexec_b64 s[8:9], vcc
	s_cbranch_execz .LBB0_1495
	s_add_u32 s14, s74, 0x1e350200
	s_addc_u32 s15, s75, 0
	s_mov_b32 s13, 1
	s_mov_b64 s[18:19], 0
	v_mov_b32_e32 v0, 0
	s_branch .LBB0_1486

.LBB0_1553:
	s_or_b64 exec, exec, s[6:7]
	v_cvt_f32_u32_e32 v4, v2
	s_waitcnt vmcnt(0)
	v_readfirstlane_b32 s4, v3
	v_sub_u32_e32 v3, 0, v2
	v_rcp_iflag_f32_e32 v4, v4
	v_add_u32_e32 v5, s4, v1
	v_mul_f32_e32 v4, 0x4f7ffffe, v4
	v_cvt_u32_f32_e32 v4, v4
	v_mul_lo_u32 v1, v3, v4
	v_mul_hi_u32 v1, v4, v1
	v_add_u32_e32 v1, v4, v1
	v_mul_hi_u32 v1, v5, v1
	v_mul_lo_u32 v3, v1, v2
	v_sub_u32_e32 v3, v5, v3
	v_add_u32_e32 v4, 1, v1
	v_cmp_ge_u32_e32 vcc, v3, v2
	s_nop 1
	v_cndmask_b32_e32 v1, v1, v4, vcc
	v_sub_u32_e32 v4, v3, v2
	v_cndmask_b32_e32 v3, v3, v4, vcc
	v_add_u32_e32 v4, 1, v1
	v_cmp_ge_u32_e32 vcc, v3, v2
	v_add_u32_e32 v3, 1, v5
	s_nop 0
	v_cndmask_b32_e32 v1, v1, v4, vcc
	v_mul_lo_u32 v4, v2, v1
	v_add_u32_e32 v2, v4, v2
	v_cmp_ne_u32_e32 vcc, v3, v2
	s_and_saveexec_b64 s[4:5], vcc
	s_xor_b64 s[4:5], exec, s[4:5]
	s_cbranch_execz .LBB0_1567
	s_waitcnt lgkmcnt(0)
	v_mov_b32_e32 v0, 0
	s_add_u32 s16, s74, 0x1e353500
	s_addc_u32 s17, s75, 0
	global_load_dword v0, v0, s[16:17] sc1
	s_waitcnt vmcnt(0)
	v_cmp_eq_u32_e32 vcc, v0, v1
	s_and_saveexec_b64 s[6:7], vcc
	s_cbranch_execz .LBB0_1566
	s_add_u32 s8, s74, 0x1e350200
	s_addc_u32 s9, s75, 0
	s_mov_b32 s13, 1
	s_mov_b64 s[18:19], 0
	v_mov_b32_e32 v0, 0
	s_branch .LBB0_1557

.LBB0_1630:
	s_or_b64 exec, exec, s[8:9]
	v_cvt_f32_u32_e32 v4, v2
	s_waitcnt vmcnt(0)
	v_readfirstlane_b32 s4, v3
	v_sub_u32_e32 v3, 0, v2
	v_rcp_iflag_f32_e32 v4, v4
	v_add_u32_e32 v5, s4, v1
	v_mul_f32_e32 v4, 0x4f7ffffe, v4
	v_cvt_u32_f32_e32 v4, v4
	v_mul_lo_u32 v1, v3, v4
	v_mul_hi_u32 v1, v4, v1
	v_add_u32_e32 v1, v4, v1
	v_mul_hi_u32 v1, v5, v1
	v_mul_lo_u32 v3, v1, v2
	v_sub_u32_e32 v3, v5, v3
	v_add_u32_e32 v4, 1, v1
	v_cmp_ge_u32_e32 vcc, v3, v2
	s_nop 1
	v_cndmask_b32_e32 v1, v1, v4, vcc
	v_sub_u32_e32 v4, v3, v2
	v_cndmask_b32_e32 v3, v3, v4, vcc
	v_add_u32_e32 v4, 1, v1
	v_cmp_ge_u32_e32 vcc, v3, v2
	v_add_u32_e32 v3, 1, v5
	s_nop 0
	v_cndmask_b32_e32 v1, v1, v4, vcc
	v_mul_lo_u32 v4, v2, v1
	v_add_u32_e32 v2, v4, v2
	v_cmp_ne_u32_e32 vcc, v3, v2
	s_and_saveexec_b64 s[4:5], vcc
	s_xor_b64 s[4:5], exec, s[4:5]
	s_cbranch_execz .LBB0_1644
	s_waitcnt lgkmcnt(0)
	v_mov_b32_e32 v0, 0
	s_add_u32 s16, s74, 0x1e353500
	s_addc_u32 s17, s75, 0
	global_load_dword v0, v0, s[16:17] sc1
	s_waitcnt vmcnt(0)
	v_cmp_eq_u32_e32 vcc, v0, v1
	s_and_saveexec_b64 s[8:9], vcc
	s_cbranch_execz .LBB0_1643
	s_add_u32 s14, s74, 0x1e350200
	s_addc_u32 s15, s75, 0
	s_mov_b32 s13, 1
	s_mov_b64 s[18:19], 0
	v_mov_b32_e32 v0, 0
	s_branch .LBB0_1634
